# v17 plus XCD-local unit order for the cross-attention score/output GEMMs (each XCD works on 8 row panels x 4 heads per round instead of 32 row panels x 1 head)
# speedup vs baseline: 1.0051x; 1.0051x over previous
;     __device__ __forceinline__ bool next(int i, Unit& u) const {
;         const int L = i * G + c; if (L >= 1024 + 128) return false;
;         int row0, bb, hp;
;         if (L < 1024) { const int pm = L >> 2; hp = L & 3; row0 = pm * BM; bb = pm >> 4; u.vlo = 0; u.vhi = 0x7fffffff; }
;         else { const int s = L - 1024, b = s >> 2; hp = s & 3; const int r = MP + DSEQ * b; row0 = r < M - BM ? r : M - BM; bb = NB + b; u.vlo = r; u.vhi = r + DSEQ; }
;         u.a = A + (size_t)row0 * D * 2;
;         u.b = W + (MODE == 0 ? (size_t)((bb * 4 + hp) * 256) : (size_t)(VW_ROW0 + bb * 1024 + hp * 256)) * D * 2;
;         u.row0 = row0; u.col0 = hp * 256; u.aux = 0; return true;
; PHASE ph_cascore(int layer_) {
;     ...
;     pg8::GemmP g{D, D, D}; pg8::SchedCA2<0> S{(const char*)(ws + WS_HB), (const char*)(ws + ca_base(layer)), F.G, F.bx, ca_vwrow0(layer)};
;     pg8::EpiSoftmax E{(bf16_t*)(ws + WS_KB), XCH_OFF, (const float*)(ws + WS_SS) + (size_t)(layer == 0 ? 1 : 4) * M, 0.0625f * LOG2E};
;     pg8::gemm_phase(F.lds + RING_OFF, g, S, E, F.tid);
.LBB0_976:
	s_or_b64 exec, exec, s[0:1]
	s_waitcnt vmcnt(0)
	s_barrier
	s_load_dword s34, s[76:77], 0x0
	s_and_b32 s35, s82, 7
	s_lshl_b32 s35, s35, 5
	s_lshr_b32 s36, s82, 3
	s_add_i32 s35, s35, s36
	s_mov_b64 s[0:1], s[84:85]
	v_readfirstlane_b32 s2, v0
	s_lshl_b32 s2, s2, 6
	s_waitcnt lgkmcnt(0)
	s_mov_b32 s36, s34
	s_load_dwordx2 s[8:9], s[0:1], 0xd0
	s_and_b32 s2, s2, 0x1c0
	v_add_u32_e32 v0, s2, v8
	v_readlane_b32 s2, v255, 18
	v_readfirstlane_b32 s16, v0
	s_waitcnt lgkmcnt(0)
	s_add_u32 s37, s8, 0xac00000
	s_addc_u32 s38, s9, 0
	s_cmp_eq_u32 s2, 0
	s_cselect_b64 s[2:3], -1, 0
	s_and_b64 s[4:5], s[2:3], exec
	s_mov_b32 s4, 0x2d400000
	s_cselect_b32 s4, 0x13000000, s4
	s_add_u32 s39, s8, s4
	s_addc_u32 s40, s9, 0
	s_cmpk_lt_i32 s35, 0x480
	s_cselect_b64 s[10:11], -1, 0
	s_cmpk_gt_i32 s35, 0x47f
	s_cbranch_scc1 .LBB0_983
	s_cmpk_gt_i32 s35, 0x3ff
	s_mov_b64 s[12:13], -1
	s_cbranch_scc0 .LBB0_979
	s_add_i32 s4, s35, 0xfffffc00
	s_lshr_b32 s5, s4, 2
	s_lshl_b32 s12, s5, 6
	s_add_i32 s44, s12, 0x10000
	s_min_u32 s4, s44, 0x10700
	s_add_i32 s14, s5, 16
	s_add_i32 s43, s12, 0x10040
	s_mov_b64 s[12:13], 0

;     __device__ __forceinline__ bool next(int i, Unit& u) const {
;         const int L = i * G + c; if (L >= 1024 + 128) return false;
;         int row0, bb, hp;
;         if (L < 1024) { const int pm = L >> 2; hp = L & 3; row0 = pm * BM; bb = pm >> 4; u.vlo = 0; u.vhi = 0x7fffffff; }
;         else { const int s = L - 1024, b = s >> 2; hp = s & 3; const int r = MP + DSEQ * b; row0 = r < M - BM ? r : M - BM; bb = NB + b; u.vlo = r; u.vhi = r + DSEQ; }
;         u.a = A + (size_t)row0 * D * 2;
;         u.b = W + (MODE == 0 ? (size_t)((bb * 4 + hp) * 256) : (size_t)(VW_ROW0 + bb * 1024 + hp * 256)) * D * 2;
;         u.row0 = row0; u.col0 = hp * 256; u.aux = 0; return true;
.LBB0_989:
	s_add_i32 s48, s48, 1
	s_mul_i32 s5, s48, s36
	s_add_i32 s5, s5, s35
	s_cmpk_lt_i32 s5, 0x400
	s_cbranch_scc1 .Lcs_map_done
	s_cmpk_gt_i32 s5, 0x4ff
	s_cbranch_scc1 .Lcs_map_done
	s_and_b32 s20, s82, 7
	s_lshl_b32 s20, s20, 4
	s_lshr_b32 s21, s82, 3
	s_add_i32 s20, s20, s21
	s_addk_i32 s20, 0x400
	s_cmp_lt_u32 s82, 0x80
	s_cselect_b32 s5, s20, 0x480
.Lcs_map_done:
	s_cmpk_lt_i32 s5, 0x480
	s_cselect_b64 s[20:21], -1, 0
	s_cmpk_gt_i32 s5, 0x47f
	s_cbranch_scc1 .LBB0_995
	s_cmpk_gt_i32 s5, 0x3ff
	s_mov_b64 s[22:23], -1
	s_cbranch_scc0 .LBB0_992
	s_add_i32 s18, s5, 0xfffffc00
	s_lshr_b32 s19, s18, 2
	s_lshl_b32 s22, s19, 6
	s_add_i32 s58, s22, 0x10000
	s_min_u32 s18, s58, 0x10700
	s_add_i32 s24, s19, 16
	s_add_i32 s54, s22, 0x10040
	s_mov_b64 s[22:23], 0

;     __device__ __forceinline__ bool next(int i, Unit& u) const {
;         const int L = i * G + c; if (L >= 1024 + 128) return false;
;         int row0, bb, hp;
;         if (L < 1024) { const int pm = L >> 2; hp = L & 3; row0 = pm * BM; bb = pm >> 4; u.vlo = 0; u.vhi = 0x7fffffff; }
;         else { const int s = L - 1024, b = s >> 2; hp = s & 3; const int r = MP + DSEQ * b; row0 = r < M - BM ? r : M - BM; bb = NB + b; u.vlo = r; u.vhi = r + DSEQ; }
;         u.a = A + (size_t)row0 * D * 2;
;         u.b = W + (MODE == 0 ? (size_t)((bb * 4 + hp) * 256) : (size_t)(VW_ROW0 + bb * 1024 + hp * 256)) * D * 2;
;         u.row0 = row0; u.col0 = hp * 256; u.aux = 0; return true;
; PHASE ph_caout(int layer_, float alpha) {
;     ...
;     pg8::GemmP g{D, D, D}; pg8::SchedCA2<1> S{(const char*)(ws + WS_KB), (const char*)(ws + ca_base(layer)), F.G, F.bx, ca_vwrow0(layer)};
;     pg8::EpiResid<false> E{(bf16_t*)(ws + WS_HB), (float*)(ws + WS_SS) + (size_t)(layer == 0 ? 2 : 5) * M, nullptr, alpha};
;     pg8::gemm_phase(F.lds + RING_OFF, g, S, E, F.tid);
.LBB0_1143:
	s_or_b64 exec, exec, s[0:1]
	s_waitcnt vmcnt(0)
	s_barrier
	s_load_dword s29, s[76:77], 0x0
	s_and_b32 s54, s82, 7
	s_lshl_b32 s54, s54, 5
	s_lshr_b32 s60, s82, 3
	s_add_i32 s54, s54, s60
	s_mov_b64 s[0:1], s[84:85]
	s_waitcnt lgkmcnt(0)
	s_mov_b32 s60, s29
	s_load_dwordx2 s[10:11], s[0:1], 0xd0
	v_readfirstlane_b32 s0, v0
	s_lshl_b32 s0, s0, 6
	s_and_b32 s0, s0, 0x1c0
	v_add_u32_e32 v0, s0, v8
	s_waitcnt lgkmcnt(0)
	s_add_u32 s61, s10, 0x1b400000
	s_addc_u32 s64, s11, 0
	v_readlane_b32 s0, v255, 18
	s_cmp_eq_u32 s0, 0
	s_cselect_b64 s[14:15], -1, 0
	s_and_b64 s[0:1], s[14:15], exec
	s_mov_b32 s0, 0x2d400000
	s_cselect_b32 s0, 0x13000000, s0
	s_mov_b32 s1, 0x21000
	s_cselect_b32 s65, s1, 0x10c00
	s_add_u32 s66, s10, s0
	s_addc_u32 s67, s11, 0
	s_cmpk_lt_i32 s54, 0x480
	s_cselect_b64 s[2:3], -1, 0
	s_cmpk_gt_i32 s54, 0x47f
	v_readfirstlane_b32 s1, v0
	s_cbranch_scc1 .LBB0_1150
	s_cmpk_gt_i32 s54, 0x3ff
	s_mov_b64 s[6:7], -1
	s_cbranch_scc0 .LBB0_1146
	s_add_i32 s0, s54, 0xfffffc00
	s_lshr_b32 s0, s0, 2
	s_lshl_b32 s5, s0, 6
	s_add_i32 s41, s5, 0x10000
	s_min_u32 s4, s41, 0x10700
	s_add_i32 s0, s0, 16
	s_add_i32 s40, s5, 0x10040
	s_mov_b64 s[6:7], 0

;     __device__ __forceinline__ bool next(int i, Unit& u) const {
;         const int L = i * G + c; if (L >= 1024 + 128) return false;
;         int row0, bb, hp;
;         if (L < 1024) { const int pm = L >> 2; hp = L & 3; row0 = pm * BM; bb = pm >> 4; u.vlo = 0; u.vhi = 0x7fffffff; }
;         else { const int s = L - 1024, b = s >> 2; hp = s & 3; const int r = MP + DSEQ * b; row0 = r < M - BM ? r : M - BM; bb = NB + b; u.vlo = r; u.vhi = r + DSEQ; }
;         u.a = A + (size_t)row0 * D * 2;
;         u.b = W + (MODE == 0 ? (size_t)((bb * 4 + hp) * 256) : (size_t)(VW_ROW0 + bb * 1024 + hp * 256)) * D * 2;
;         u.row0 = row0; u.col0 = hp * 256; u.aux = 0; return true;
.LBB0_1156:
	s_add_i32 s89, s89, 1
	s_mul_i32 s12, s89, s60
	s_add_i32 s12, s12, s54
	s_cmpk_lt_i32 s12, 0x400
	s_cbranch_scc1 .Lco_map_done
	s_cmpk_gt_i32 s12, 0x4ff
	s_cbranch_scc1 .Lco_map_done
	v_readlane_b32 s87, v255, 0
	s_nop 0
	s_and_b32 s86, s87, 7
	s_lshl_b32 s86, s86, 4
	s_lshr_b32 s12, s87, 3
	s_add_i32 s86, s86, s12
	s_addk_i32 s86, 0x400
	s_cmp_lt_u32 s87, 0x80
	s_cselect_b32 s12, s86, 0x480
.Lco_map_done:
	s_cmpk_lt_i32 s12, 0x480
	s_cselect_b64 s[86:87], -1, 0
	s_cmpk_gt_i32 s12, 0x47f
	s_cbranch_scc1 .LBB0_1162
	s_cmpk_gt_i32 s12, 0x3ff
	s_mov_b64 s[10:11], -1
	s_cbranch_scc0 .LBB0_1159
	s_add_i32 s1, s12, 0xfffffc00
	s_lshr_b32 s1, s1, 2
	s_lshl_b32 s10, s1, 6
	s_add_i32 s56, s10, 0x10000
	s_min_u32 s84, s56, 0x10700
	s_add_i32 s13, s1, 16
	s_add_i32 s1, s10, 0x10040
	s_mov_b64 s[10:11], 0
